# v18 + z-gate GEMM1 epilogue stores via v_permlane16_swap register transpose, no LDS stage
# baseline (speedup 1.0000x reference)
.LBB0_581:
	s_andn2_b64 vcc, exec, s[8:9]
	s_cbranch_vccnz .LBB0_588
	s_cmp_eq_u32 s58, 13
	s_mov_b64 s[8:9], -1
	s_cbranch_scc1 .LBB0_584
	v_mul_f32_e32 v80, 0xbfb8aa3b, v12
	v_exp_f32_e32 v80, v80
	v_mul_f32_e32 v82, 0xbfb8aa3b, v13
	v_exp_f32_e32 v83, v82
	v_mul_f32_e32 v0, 0xbfb8aa3b, v8
	v_add_f32_e32 v80, 1.0, v80
	v_rcp_f32_e32 v82, v80
	v_add_f32_e32 v80, 1.0, v83
	v_mul_f32_e32 v83, 0xbfb8aa3b, v14
	v_exp_f32_e32 v84, v83
	v_mul_f32_e32 v83, 0xbfb8aa3b, v15
	v_exp_f32_e32 v85, v83
	v_rcp_f32_e32 v83, v80
	v_add_f32_e32 v80, 1.0, v84
	v_rcp_f32_e32 v84, v80
	v_add_f32_e32 v80, 1.0, v85
	v_mul_f32_e32 v85, 0xbfb8aa3b, v152
	v_exp_f32_e32 v86, v85
	v_mul_f32_e32 v85, 0xbfb8aa3b, v153
	v_exp_f32_e32 v87, v85
	v_rcp_f32_e32 v85, v80
	v_add_f32_e32 v80, 1.0, v86
	v_mul_f32_e32 v1, 0xbfb8aa3b, v9
	v_mul_f32_e32 v2, 0xbfb8aa3b, v10
	v_mul_f32_e32 v3, 0xbfb8aa3b, v11
	v_rcp_f32_e32 v86, v80
	v_add_f32_e32 v80, 1.0, v87
	v_mul_f32_e32 v87, 0xbfb8aa3b, v154
	v_exp_f32_e32 v0, v0
	v_exp_f32_e32 v1, v1
	v_exp_f32_e32 v2, v2
	v_exp_f32_e32 v3, v3
	v_mul_f32_e32 v4, 0xbfb8aa3b, v156
	v_mul_f32_e32 v5, 0xbfb8aa3b, v157
	v_mul_f32_e32 v6, 0xbfb8aa3b, v158
	v_mul_f32_e32 v7, 0xbfb8aa3b, v159
	v_exp_f32_e32 v160, v87
	v_mul_f32_e32 v87, 0xbfb8aa3b, v155
	v_exp_f32_e32 v4, v4
	v_exp_f32_e32 v5, v5
	v_exp_f32_e32 v6, v6
	v_exp_f32_e32 v7, v7
	v_exp_f32_e32 v161, v87
	v_add_f32_e32 v0, 1.0, v0
	v_add_f32_e32 v1, 1.0, v1
	v_add_f32_e32 v2, 1.0, v2
	v_add_f32_e32 v3, 1.0, v3
	v_rcp_f32_e32 v87, v80
	v_add_f32_e32 v80, 1.0, v160
	v_rcp_f32_e32 v0, v0
	v_rcp_f32_e32 v1, v1
	v_rcp_f32_e32 v2, v2
	v_rcp_f32_e32 v3, v3
	v_add_f32_e32 v4, 1.0, v4
	v_add_f32_e32 v5, 1.0, v5
	v_add_f32_e32 v6, 1.0, v6
	v_add_f32_e32 v7, 1.0, v7
	v_rcp_f32_e32 v162, v80
	v_add_f32_e32 v80, 1.0, v161
	v_rcp_f32_e32 v4, v4
	v_rcp_f32_e32 v5, v5
	v_rcp_f32_e32 v6, v6
	v_rcp_f32_e32 v7, v7
	v_rcp_f32_e32 v163, v80
	v_pk_mul_f32 v[0:1], v[8:9], v[0:1]
	v_pk_mul_f32 v[2:3], v[10:11], v[2:3]
	v_mad_u32_u24 v80, v195, s77, v196
	v_pk_mul_f32 v[4:5], v[156:157], v[4:5]
	v_pk_mul_f32 v[6:7], v[158:159], v[6:7]
	v_pk_mul_f32 v[82:83], v[12:13], v[82:83]
	v_pk_mul_f32 v[84:85], v[14:15], v[84:85]
	v_pk_mul_f32 v[160:161], v[152:153], v[86:87]
	v_pk_mul_f32 v[162:163], v[154:155], v[162:163]
	v_cvt_pk_bf16_f32 v0, v0, v1
	v_cvt_pk_bf16_f32 v1, v2, v3
	v_cvt_pk_bf16_f32 v2, v4, v5
	v_cvt_pk_bf16_f32 v3, v6, v7
	v_cvt_pk_bf16_f32 v4, v82, v83
	v_cvt_pk_bf16_f32 v5, v84, v85
	v_cvt_pk_bf16_f32 v6, v160, v161
	v_cvt_pk_bf16_f32 v7, v162, v163
	v_readlane_b32 s100, v254, 33
	s_lshl_b32 s101, s16, 8
	s_lshl_b64 s[8:9], s[48:49], 11
	s_or_b32 s100, s100, s101
	s_lshl_b32 s100, s100, 1
	s_add_u32 s100, s100, 0x58ff200
	s_add_u32 s100, s100, s18
	s_addc_u32 s101, s19, 0
	s_add_u32 s100, s100, s8
	s_addc_u32 s101, s101, s9
	v_and_b32_e32 v82, 15, v194
	v_lshlrev_b32_e32 v82, 11, v82
	v_and_b32_e32 v83, 16, v194
	v_lshl_or_b32 v82, v83, 1, v82
	v_and_b32_e32 v83, 32, v194
	v_lshrrev_b32_e32 v83, 1, v83
	v_or_b32_e32 v82, v82, v83
	s_nop 1
	v_permlane16_swap_b32_e32 v0, v2
	v_permlane16_swap_b32_e32 v1, v3
	v_permlane16_swap_b32_e32 v4, v6
	v_permlane16_swap_b32_e32 v5, v7
	global_store_dwordx4 v82, v[0:3], s[100:101] sc1
	global_store_dwordx4 v82, v[4:7], s[100:101] offset:64 sc1
	s_nop 1
	s_mov_b64 s[8:9], 0

.LBB0_641:
	v_mov_b64_e32 v[14:15], v[6:7]
	s_andn2_b64 vcc, exec, s[44:45]
	v_mov_b64_e32 v[12:13], v[4:5]
	v_mov_b64_e32 v[10:11], v[2:3]
	v_mov_b64_e32 v[8:9], v[0:1]
	s_cbranch_vccnz .LBB0_650
	s_cmp_lg_u32 s58, 13
	s_mov_b64 s[44:45], -1
	s_cbranch_scc0 .LBB0_646
	v_mul_f32_e32 v80, 0xbfb8aa3b, v152
	v_exp_f32_e32 v80, v80
	v_mul_f32_e32 v87, 0xbfb8aa3b, v153
	v_exp_f32_e32 v87, v87
	v_mul_f32_e32 v165, 0xbfb8aa3b, v155
	v_add_f32_e32 v80, 1.0, v80
	v_rcp_f32_e32 v164, v80
	v_add_f32_e32 v80, 1.0, v87
	v_mul_f32_e32 v87, 0xbfb8aa3b, v154
	v_exp_f32_e32 v87, v87
	v_exp_f32_e32 v167, v165
	v_rcp_f32_e32 v165, v80
	v_mul_f32_e32 v8, 0xbfb8aa3b, v82
	v_add_f32_e32 v80, 1.0, v87
	v_mul_f32_e32 v87, 0xbfb8aa3b, v156
	v_rcp_f32_e32 v166, v80
	v_add_f32_e32 v80, 1.0, v167
	v_exp_f32_e32 v87, v87
	v_mul_f32_e32 v167, 0xbfb8aa3b, v157
	v_exp_f32_e32 v169, v167
	v_mul_f32_e32 v9, 0xbfb8aa3b, v83
	v_mul_f32_e32 v10, 0xbfb8aa3b, v84
	v_mul_f32_e32 v11, 0xbfb8aa3b, v85
	v_rcp_f32_e32 v167, v80
	v_add_f32_e32 v80, 1.0, v87
	v_mul_f32_e32 v87, 0xbfb8aa3b, v158
	v_exp_f32_e32 v8, v8
	v_exp_f32_e32 v9, v9
	v_exp_f32_e32 v10, v10
	v_exp_f32_e32 v11, v11
	v_mul_f32_e32 v12, 0xbfb8aa3b, v160
	v_mul_f32_e32 v13, 0xbfb8aa3b, v161
	v_mul_f32_e32 v14, 0xbfb8aa3b, v162
	v_mul_f32_e32 v15, 0xbfb8aa3b, v163
	v_rcp_f32_e32 v168, v80
	v_add_f32_e32 v80, 1.0, v169
	v_exp_f32_e32 v87, v87
	v_mul_f32_e32 v169, 0xbfb8aa3b, v159
	v_exp_f32_e32 v12, v12
	v_exp_f32_e32 v13, v13
	v_exp_f32_e32 v14, v14
	v_exp_f32_e32 v15, v15
	v_exp_f32_e32 v171, v169
	v_add_f32_e32 v8, 1.0, v8
	v_add_f32_e32 v9, 1.0, v9
	v_add_f32_e32 v10, 1.0, v10
	v_add_f32_e32 v11, 1.0, v11
	v_rcp_f32_e32 v169, v80
	v_add_f32_e32 v80, 1.0, v87
	v_rcp_f32_e32 v8, v8
	v_rcp_f32_e32 v9, v9
	v_rcp_f32_e32 v10, v10
	v_rcp_f32_e32 v11, v11
	v_add_f32_e32 v12, 1.0, v12
	v_add_f32_e32 v13, 1.0, v13
	v_add_f32_e32 v14, 1.0, v14
	v_add_f32_e32 v15, 1.0, v15
	v_rcp_f32_e32 v170, v80
	v_add_f32_e32 v80, 1.0, v171
	v_rcp_f32_e32 v12, v12
	v_rcp_f32_e32 v13, v13
	v_rcp_f32_e32 v14, v14
	v_rcp_f32_e32 v15, v15
	v_rcp_f32_e32 v171, v80
	v_pk_mul_f32 v[8:9], v[82:83], v[8:9]
	v_pk_mul_f32 v[10:11], v[84:85], v[10:11]
	v_mad_u32_u24 v80, v202, s77, v196
	v_ashrrev_i32_e32 v87, 31, v86
	v_readlane_b32 s36, v254, 54
	s_lshl_b32 s0, s16, 8
	v_readlane_b32 s3, v254, 33
	v_pk_mul_f32 v[12:13], v[160:161], v[12:13]
	v_pk_mul_f32 v[14:15], v[162:163], v[14:15]
	v_pk_mul_f32 v[164:165], v[152:153], v[164:165]
	v_pk_mul_f32 v[166:167], v[154:155], v[166:167]
	v_pk_mul_f32 v[168:169], v[156:157], v[168:169]
	v_pk_mul_f32 v[170:171], v[158:159], v[170:171]
	v_cvt_pk_bf16_f32 v8, v8, v9
	v_cvt_pk_bf16_f32 v9, v10, v11
	v_cvt_pk_bf16_f32 v10, v12, v13
	v_cvt_pk_bf16_f32 v11, v14, v15
	v_cvt_pk_bf16_f32 v12, v164, v165
	v_cvt_pk_bf16_f32 v13, v166, v167
	v_cvt_pk_bf16_f32 v14, v168, v169
	v_cvt_pk_bf16_f32 v15, v170, v171
	v_readlane_b32 s100, v254, 33
	s_lshl_b32 s101, s16, 8
	v_readlane_b32 s36, v254, 54
	v_readlane_b32 s37, v254, 55
	s_or_b32 s100, s100, s101
	s_lshl_b32 s100, s100, 1
	s_add_u32 s100, s100, 0x58ff200
	s_add_u32 s100, s100, s18
	s_addc_u32 s101, s19, 0
	s_add_u32 s100, s100, s36
	s_addc_u32 s101, s101, s37
	v_and_b32_e32 v164, 15, v194
	v_lshlrev_b32_e32 v164, 11, v164
	v_and_b32_e32 v165, 16, v194
	v_lshl_or_b32 v164, v165, 1, v164
	v_and_b32_e32 v165, 32, v194
	v_lshrrev_b32_e32 v165, 1, v165
	v_or_b32_e32 v164, v164, v165
	v_or_b32_e32 v164, 0x8000, v164
	s_nop 1
	v_permlane16_swap_b32_e32 v8, v10
	v_permlane16_swap_b32_e32 v9, v11
	v_permlane16_swap_b32_e32 v12, v14
	v_permlane16_swap_b32_e32 v13, v15
	global_store_dwordx4 v164, v[8:11], s[100:101] sc1
	global_store_dwordx4 v164, v[12:15], s[100:101] offset:64 sc1
	s_nop 1
	s_mov_b64 s[44:45], 0

.LBB0_718:
	v_mov_b64_e32 v[0:1], v[8:9]
	s_andn2_b64 vcc, exec, s[44:45]
	v_mov_b64_e32 v[2:3], v[10:11]
	v_mov_b64_e32 v[4:5], v[12:13]
	v_mov_b64_e32 v[6:7], v[14:15]
	s_cbranch_vccnz .LBB0_725
	s_cmp_lg_u32 s58, 13
	s_mov_b64 s[44:45], -1
	s_cbranch_scc0 .LBB0_721
	v_mul_f32_e32 v80, 0xbfb8aa3b, v152
	v_exp_f32_e32 v80, v80
	v_mul_f32_e32 v87, 0xbfb8aa3b, v153
	v_exp_f32_e32 v87, v87
	v_mul_f32_e32 v165, 0xbfb8aa3b, v155
	v_add_f32_e32 v80, 1.0, v80
	v_rcp_f32_e32 v164, v80
	v_add_f32_e32 v80, 1.0, v87
	v_mul_f32_e32 v87, 0xbfb8aa3b, v154
	v_exp_f32_e32 v87, v87
	v_exp_f32_e32 v167, v165
	v_rcp_f32_e32 v165, v80
	v_mul_f32_e32 v0, 0xbfb8aa3b, v82
	v_add_f32_e32 v80, 1.0, v87
	v_mul_f32_e32 v87, 0xbfb8aa3b, v156
	v_rcp_f32_e32 v166, v80
	v_add_f32_e32 v80, 1.0, v167
	v_exp_f32_e32 v87, v87
	v_mul_f32_e32 v167, 0xbfb8aa3b, v157
	v_exp_f32_e32 v169, v167
	v_mul_f32_e32 v1, 0xbfb8aa3b, v83
	v_mul_f32_e32 v2, 0xbfb8aa3b, v84
	v_mul_f32_e32 v3, 0xbfb8aa3b, v85
	v_rcp_f32_e32 v167, v80
	v_add_f32_e32 v80, 1.0, v87
	v_mul_f32_e32 v87, 0xbfb8aa3b, v158
	v_exp_f32_e32 v0, v0
	v_exp_f32_e32 v1, v1
	v_exp_f32_e32 v2, v2
	v_exp_f32_e32 v3, v3
	v_mul_f32_e32 v4, 0xbfb8aa3b, v160
	v_mul_f32_e32 v5, 0xbfb8aa3b, v161
	v_mul_f32_e32 v6, 0xbfb8aa3b, v162
	v_mul_f32_e32 v7, 0xbfb8aa3b, v163
	v_rcp_f32_e32 v168, v80
	v_add_f32_e32 v80, 1.0, v169
	v_exp_f32_e32 v87, v87
	v_mul_f32_e32 v169, 0xbfb8aa3b, v159
	v_exp_f32_e32 v4, v4
	v_exp_f32_e32 v5, v5
	v_exp_f32_e32 v6, v6
	v_exp_f32_e32 v7, v7
	v_exp_f32_e32 v171, v169
	v_add_f32_e32 v0, 1.0, v0
	v_add_f32_e32 v1, 1.0, v1
	v_add_f32_e32 v2, 1.0, v2
	v_add_f32_e32 v3, 1.0, v3
	v_rcp_f32_e32 v169, v80
	v_add_f32_e32 v80, 1.0, v87
	v_rcp_f32_e32 v0, v0
	v_rcp_f32_e32 v1, v1
	v_rcp_f32_e32 v2, v2
	v_rcp_f32_e32 v3, v3
	v_add_f32_e32 v4, 1.0, v4
	v_add_f32_e32 v5, 1.0, v5
	v_add_f32_e32 v6, 1.0, v6
	v_add_f32_e32 v7, 1.0, v7
	v_rcp_f32_e32 v170, v80
	v_add_f32_e32 v80, 1.0, v171
	v_rcp_f32_e32 v4, v4
	v_rcp_f32_e32 v5, v5
	v_rcp_f32_e32 v6, v6
	v_rcp_f32_e32 v7, v7
	v_rcp_f32_e32 v171, v80
	v_pk_mul_f32 v[0:1], v[82:83], v[0:1]
	v_pk_mul_f32 v[2:3], v[84:85], v[2:3]
	v_mad_u32_u24 v80, v195, s77, v196
	v_pk_mul_f32 v[4:5], v[160:161], v[4:5]
	v_pk_mul_f32 v[6:7], v[162:163], v[6:7]
	v_pk_mul_f32 v[164:165], v[152:153], v[164:165]
	v_pk_mul_f32 v[166:167], v[154:155], v[166:167]
	v_pk_mul_f32 v[168:169], v[156:157], v[168:169]
	v_pk_mul_f32 v[170:171], v[158:159], v[170:171]
	v_cvt_pk_bf16_f32 v0, v0, v1
	v_cvt_pk_bf16_f32 v1, v2, v3
	v_cvt_pk_bf16_f32 v2, v4, v5
	v_cvt_pk_bf16_f32 v3, v6, v7
	v_cvt_pk_bf16_f32 v4, v164, v165
	v_cvt_pk_bf16_f32 v5, v166, v167
	v_cvt_pk_bf16_f32 v6, v168, v169
	v_cvt_pk_bf16_f32 v7, v170, v171
	v_readlane_b32 s100, v254, 33
	s_lshl_b32 s101, s16, 8
	v_readlane_b32 s44, v254, 54
	v_readlane_b32 s45, v254, 55
	s_or_b32 s100, s100, s101
	s_lshl_b32 s100, s100, 1
	s_add_u32 s100, s100, 0x590f200
	s_add_u32 s100, s100, s18
	s_addc_u32 s101, s19, 0
	s_add_u32 s100, s100, s44
	s_addc_u32 s101, s101, s45
	v_and_b32_e32 v164, 15, v194
	v_lshlrev_b32_e32 v164, 11, v164
	v_and_b32_e32 v165, 16, v194
	v_lshl_or_b32 v164, v165, 1, v164
	v_and_b32_e32 v165, 32, v194
	v_lshrrev_b32_e32 v165, 1, v165
	v_or_b32_e32 v164, v164, v165
	s_nop 1
	v_permlane16_swap_b32_e32 v0, v2
	v_permlane16_swap_b32_e32 v1, v3
	v_permlane16_swap_b32_e32 v4, v6
	v_permlane16_swap_b32_e32 v5, v7
	global_store_dwordx4 v164, v[0:3], s[100:101] sc1
	global_store_dwordx4 v164, v[4:7], s[100:101] offset:64 sc1
	s_nop 1
	s_mov_b64 s[44:45], 0

.LBB0_777:
	v_mov_b64_e32 v[14:15], v[6:7]
	s_andn2_b64 vcc, exec, s[44:45]
	v_mov_b64_e32 v[12:13], v[4:5]
	v_mov_b64_e32 v[10:11], v[2:3]
	v_mov_b64_e32 v[8:9], v[0:1]
	s_cbranch_vccnz .LBB0_786
	s_cmp_lg_u32 s58, 13
	s_mov_b64 s[44:45], -1
	s_cbranch_scc0 .LBB0_782
	v_mul_f32_e32 v80, 0xbfb8aa3b, v152
	v_exp_f32_e32 v80, v80
	v_mul_f32_e32 v87, 0xbfb8aa3b, v153
	v_exp_f32_e32 v87, v87
	v_mul_f32_e32 v165, 0xbfb8aa3b, v155
	v_add_f32_e32 v80, 1.0, v80
	v_rcp_f32_e32 v164, v80
	v_add_f32_e32 v80, 1.0, v87
	v_mul_f32_e32 v87, 0xbfb8aa3b, v154
	v_exp_f32_e32 v87, v87
	v_exp_f32_e32 v167, v165
	v_rcp_f32_e32 v165, v80
	v_mul_f32_e32 v8, 0xbfb8aa3b, v82
	v_add_f32_e32 v80, 1.0, v87
	v_mul_f32_e32 v87, 0xbfb8aa3b, v156
	v_rcp_f32_e32 v166, v80
	v_add_f32_e32 v80, 1.0, v167
	v_exp_f32_e32 v87, v87
	v_mul_f32_e32 v167, 0xbfb8aa3b, v157
	v_exp_f32_e32 v169, v167
	v_mul_f32_e32 v9, 0xbfb8aa3b, v83
	v_mul_f32_e32 v10, 0xbfb8aa3b, v84
	v_mul_f32_e32 v11, 0xbfb8aa3b, v85
	v_rcp_f32_e32 v167, v80
	v_add_f32_e32 v80, 1.0, v87
	v_mul_f32_e32 v87, 0xbfb8aa3b, v158
	v_exp_f32_e32 v8, v8
	v_exp_f32_e32 v9, v9
	v_exp_f32_e32 v10, v10
	v_exp_f32_e32 v11, v11
	v_mul_f32_e32 v12, 0xbfb8aa3b, v160
	v_mul_f32_e32 v13, 0xbfb8aa3b, v161
	v_mul_f32_e32 v14, 0xbfb8aa3b, v162
	v_mul_f32_e32 v15, 0xbfb8aa3b, v163
	v_rcp_f32_e32 v168, v80
	v_add_f32_e32 v80, 1.0, v169
	v_exp_f32_e32 v87, v87
	v_mul_f32_e32 v169, 0xbfb8aa3b, v159
	v_exp_f32_e32 v12, v12
	v_exp_f32_e32 v13, v13
	v_exp_f32_e32 v14, v14
	v_exp_f32_e32 v15, v15
	v_exp_f32_e32 v171, v169
	v_add_f32_e32 v8, 1.0, v8
	v_add_f32_e32 v9, 1.0, v9
	v_add_f32_e32 v10, 1.0, v10
	v_add_f32_e32 v11, 1.0, v11
	v_rcp_f32_e32 v169, v80
	v_add_f32_e32 v80, 1.0, v87
	v_rcp_f32_e32 v8, v8
	v_rcp_f32_e32 v9, v9
	v_rcp_f32_e32 v10, v10
	v_rcp_f32_e32 v11, v11
	v_add_f32_e32 v12, 1.0, v12
	v_add_f32_e32 v13, 1.0, v13
	v_add_f32_e32 v14, 1.0, v14
	v_add_f32_e32 v15, 1.0, v15
	v_rcp_f32_e32 v170, v80
	v_add_f32_e32 v80, 1.0, v171
	v_rcp_f32_e32 v12, v12
	v_rcp_f32_e32 v13, v13
	v_rcp_f32_e32 v14, v14
	v_rcp_f32_e32 v15, v15
	v_rcp_f32_e32 v171, v80
	v_pk_mul_f32 v[8:9], v[82:83], v[8:9]
	v_pk_mul_f32 v[10:11], v[84:85], v[10:11]
	v_mad_u32_u24 v80, v202, s77, v196
	v_ashrrev_i32_e32 v87, 31, v86
	v_readlane_b32 s36, v254, 54
	s_lshl_b32 s0, s16, 8
	v_readlane_b32 s3, v254, 33
	v_pk_mul_f32 v[12:13], v[160:161], v[12:13]
	v_pk_mul_f32 v[14:15], v[162:163], v[14:15]
	v_pk_mul_f32 v[164:165], v[152:153], v[164:165]
	v_pk_mul_f32 v[166:167], v[154:155], v[166:167]
	v_pk_mul_f32 v[168:169], v[156:157], v[168:169]
	v_pk_mul_f32 v[170:171], v[158:159], v[170:171]
	v_cvt_pk_bf16_f32 v8, v8, v9
	v_cvt_pk_bf16_f32 v9, v10, v11
	v_cvt_pk_bf16_f32 v10, v12, v13
	v_cvt_pk_bf16_f32 v11, v14, v15
	v_cvt_pk_bf16_f32 v12, v164, v165
	v_cvt_pk_bf16_f32 v13, v166, v167
	v_cvt_pk_bf16_f32 v14, v168, v169
	v_cvt_pk_bf16_f32 v15, v170, v171
	v_readlane_b32 s100, v254, 33
	s_lshl_b32 s101, s16, 8
	v_readlane_b32 s36, v254, 54
	v_readlane_b32 s37, v254, 55
	s_or_b32 s100, s100, s101
	s_lshl_b32 s100, s100, 1
	s_add_u32 s100, s100, 0x590f200
	s_add_u32 s100, s100, s18
	s_addc_u32 s101, s19, 0
	s_add_u32 s100, s100, s36
	s_addc_u32 s101, s101, s37
	v_and_b32_e32 v164, 15, v194
	v_lshlrev_b32_e32 v164, 11, v164
	v_and_b32_e32 v165, 16, v194
	v_lshl_or_b32 v164, v165, 1, v164
	v_and_b32_e32 v165, 32, v194
	v_lshrrev_b32_e32 v165, 1, v165
	v_or_b32_e32 v164, v164, v165
	v_or_b32_e32 v164, 0x8000, v164
	s_nop 1
	v_permlane16_swap_b32_e32 v8, v10
	v_permlane16_swap_b32_e32 v9, v11
	v_permlane16_swap_b32_e32 v12, v14
	v_permlane16_swap_b32_e32 v13, v15
	global_store_dwordx4 v164, v[8:11], s[100:101] sc1
	global_store_dwordx4 v164, v[12:15], s[100:101] offset:64 sc1
	s_nop 1
	s_mov_b64 s[44:45], 0

.LBB0_854:
	v_mov_b64_e32 v[0:1], v[8:9]
	s_andn2_b64 vcc, exec, s[44:45]
	v_mov_b64_e32 v[2:3], v[10:11]
	v_mov_b64_e32 v[4:5], v[12:13]
	v_mov_b64_e32 v[6:7], v[14:15]
	s_cbranch_vccnz .LBB0_861
	s_cmp_lg_u32 s58, 13
	s_mov_b64 s[44:45], -1
	s_cbranch_scc0 .LBB0_857
	v_mul_f32_e32 v80, 0xbfb8aa3b, v152
	v_exp_f32_e32 v80, v80
	v_mul_f32_e32 v87, 0xbfb8aa3b, v153
	v_exp_f32_e32 v87, v87
	v_mul_f32_e32 v165, 0xbfb8aa3b, v155
	v_add_f32_e32 v80, 1.0, v80
	v_rcp_f32_e32 v164, v80
	v_add_f32_e32 v80, 1.0, v87
	v_mul_f32_e32 v87, 0xbfb8aa3b, v154
	v_exp_f32_e32 v87, v87
	v_exp_f32_e32 v167, v165
	v_rcp_f32_e32 v165, v80
	v_mul_f32_e32 v0, 0xbfb8aa3b, v82
	v_add_f32_e32 v80, 1.0, v87
	v_mul_f32_e32 v87, 0xbfb8aa3b, v156
	v_rcp_f32_e32 v166, v80
	v_add_f32_e32 v80, 1.0, v167
	v_exp_f32_e32 v87, v87
	v_mul_f32_e32 v167, 0xbfb8aa3b, v157
	v_exp_f32_e32 v169, v167
	v_mul_f32_e32 v1, 0xbfb8aa3b, v83
	v_mul_f32_e32 v2, 0xbfb8aa3b, v84
	v_mul_f32_e32 v3, 0xbfb8aa3b, v85
	v_rcp_f32_e32 v167, v80
	v_add_f32_e32 v80, 1.0, v87
	v_mul_f32_e32 v87, 0xbfb8aa3b, v158
	v_exp_f32_e32 v0, v0
	v_exp_f32_e32 v1, v1
	v_exp_f32_e32 v2, v2
	v_exp_f32_e32 v3, v3
	v_mul_f32_e32 v4, 0xbfb8aa3b, v160
	v_mul_f32_e32 v5, 0xbfb8aa3b, v161
	v_mul_f32_e32 v6, 0xbfb8aa3b, v162
	v_mul_f32_e32 v7, 0xbfb8aa3b, v163
	v_rcp_f32_e32 v168, v80
	v_add_f32_e32 v80, 1.0, v169
	v_exp_f32_e32 v87, v87
	v_mul_f32_e32 v169, 0xbfb8aa3b, v159
	v_exp_f32_e32 v4, v4
	v_exp_f32_e32 v5, v5
	v_exp_f32_e32 v6, v6
	v_exp_f32_e32 v7, v7
	v_exp_f32_e32 v171, v169
	v_add_f32_e32 v0, 1.0, v0
	v_add_f32_e32 v1, 1.0, v1
	v_add_f32_e32 v2, 1.0, v2
	v_add_f32_e32 v3, 1.0, v3
	v_rcp_f32_e32 v169, v80
	v_add_f32_e32 v80, 1.0, v87
	v_rcp_f32_e32 v0, v0
	v_rcp_f32_e32 v1, v1
	v_rcp_f32_e32 v2, v2
	v_rcp_f32_e32 v3, v3
	v_add_f32_e32 v4, 1.0, v4
	v_add_f32_e32 v5, 1.0, v5
	v_add_f32_e32 v6, 1.0, v6
	v_add_f32_e32 v7, 1.0, v7
	v_rcp_f32_e32 v170, v80
	v_add_f32_e32 v80, 1.0, v171
	v_rcp_f32_e32 v4, v4
	v_rcp_f32_e32 v5, v5
	v_rcp_f32_e32 v6, v6
	v_rcp_f32_e32 v7, v7
	v_rcp_f32_e32 v171, v80
	v_pk_mul_f32 v[0:1], v[82:83], v[0:1]
	v_pk_mul_f32 v[2:3], v[84:85], v[2:3]
	v_mad_u32_u24 v80, v195, s77, v196
	v_pk_mul_f32 v[4:5], v[160:161], v[4:5]
	v_pk_mul_f32 v[6:7], v[162:163], v[6:7]
	v_pk_mul_f32 v[164:165], v[152:153], v[164:165]
	v_pk_mul_f32 v[166:167], v[154:155], v[166:167]
	v_pk_mul_f32 v[168:169], v[156:157], v[168:169]
	v_pk_mul_f32 v[170:171], v[158:159], v[170:171]
	v_cvt_pk_bf16_f32 v0, v0, v1
	v_cvt_pk_bf16_f32 v1, v2, v3
	v_cvt_pk_bf16_f32 v2, v4, v5
	v_cvt_pk_bf16_f32 v3, v6, v7
	v_cvt_pk_bf16_f32 v4, v164, v165
	v_cvt_pk_bf16_f32 v5, v166, v167
	v_cvt_pk_bf16_f32 v6, v168, v169
	v_cvt_pk_bf16_f32 v7, v170, v171
	v_readlane_b32 s100, v254, 33
	s_lshl_b32 s101, s16, 8
	v_readlane_b32 s44, v254, 54
	v_readlane_b32 s45, v254, 55
	s_or_b32 s100, s100, s101
	s_lshl_b32 s100, s100, 1
	s_add_u32 s100, s100, 0x591f200
	s_add_u32 s100, s100, s18
	s_addc_u32 s101, s19, 0
	s_add_u32 s100, s100, s44
	s_addc_u32 s101, s101, s45
	v_and_b32_e32 v164, 15, v194
	v_lshlrev_b32_e32 v164, 11, v164
	v_and_b32_e32 v165, 16, v194
	v_lshl_or_b32 v164, v165, 1, v164
	v_and_b32_e32 v165, 32, v194
	v_lshrrev_b32_e32 v165, 1, v165
	v_or_b32_e32 v164, v164, v165
	s_nop 1
	v_permlane16_swap_b32_e32 v0, v2
	v_permlane16_swap_b32_e32 v1, v3
	v_permlane16_swap_b32_e32 v4, v6
	v_permlane16_swap_b32_e32 v5, v7
	global_store_dwordx4 v164, v[0:3], s[100:101] sc1
	global_store_dwordx4 v164, v[4:7], s[100:101] offset:64 sc1
	s_nop 1
	s_mov_b64 s[44:45], 0

.LBB0_913:
	v_mov_b64_e32 v[14:15], v[6:7]
	s_andn2_b64 vcc, exec, s[44:45]
	v_mov_b64_e32 v[12:13], v[4:5]
	v_mov_b64_e32 v[10:11], v[2:3]
	v_mov_b64_e32 v[8:9], v[0:1]
	s_cbranch_vccnz .LBB0_922
	s_cmp_lg_u32 s58, 13
	s_mov_b64 s[44:45], -1
	s_cbranch_scc0 .LBB0_918
	v_mul_f32_e32 v80, 0xbfb8aa3b, v152
	v_exp_f32_e32 v80, v80
	v_mul_f32_e32 v87, 0xbfb8aa3b, v153
	v_exp_f32_e32 v87, v87
	v_mul_f32_e32 v165, 0xbfb8aa3b, v155
	v_add_f32_e32 v80, 1.0, v80
	v_rcp_f32_e32 v164, v80
	v_add_f32_e32 v80, 1.0, v87
	v_mul_f32_e32 v87, 0xbfb8aa3b, v154
	v_exp_f32_e32 v87, v87
	v_exp_f32_e32 v167, v165
	v_rcp_f32_e32 v165, v80
	v_mul_f32_e32 v8, 0xbfb8aa3b, v82
	v_add_f32_e32 v80, 1.0, v87
	v_mul_f32_e32 v87, 0xbfb8aa3b, v156
	v_rcp_f32_e32 v166, v80
	v_add_f32_e32 v80, 1.0, v167
	v_exp_f32_e32 v87, v87
	v_mul_f32_e32 v167, 0xbfb8aa3b, v157
	v_exp_f32_e32 v169, v167
	v_mul_f32_e32 v9, 0xbfb8aa3b, v83
	v_mul_f32_e32 v10, 0xbfb8aa3b, v84
	v_mul_f32_e32 v11, 0xbfb8aa3b, v85
	v_rcp_f32_e32 v167, v80
	v_add_f32_e32 v80, 1.0, v87
	v_mul_f32_e32 v87, 0xbfb8aa3b, v158
	v_exp_f32_e32 v8, v8
	v_exp_f32_e32 v9, v9
	v_exp_f32_e32 v10, v10
	v_exp_f32_e32 v11, v11
	v_mul_f32_e32 v12, 0xbfb8aa3b, v160
	v_mul_f32_e32 v13, 0xbfb8aa3b, v161
	v_mul_f32_e32 v14, 0xbfb8aa3b, v162
	v_mul_f32_e32 v15, 0xbfb8aa3b, v163
	v_rcp_f32_e32 v168, v80
	v_add_f32_e32 v80, 1.0, v169
	v_exp_f32_e32 v87, v87
	v_mul_f32_e32 v169, 0xbfb8aa3b, v159
	v_exp_f32_e32 v12, v12
	v_exp_f32_e32 v13, v13
	v_exp_f32_e32 v14, v14
	v_exp_f32_e32 v15, v15
	v_exp_f32_e32 v171, v169
	v_add_f32_e32 v8, 1.0, v8
	v_add_f32_e32 v9, 1.0, v9
	v_add_f32_e32 v10, 1.0, v10
	v_add_f32_e32 v11, 1.0, v11
	v_rcp_f32_e32 v169, v80
	v_add_f32_e32 v80, 1.0, v87
	v_rcp_f32_e32 v8, v8
	v_rcp_f32_e32 v9, v9
	v_rcp_f32_e32 v10, v10
	v_rcp_f32_e32 v11, v11
	v_add_f32_e32 v12, 1.0, v12
	v_add_f32_e32 v13, 1.0, v13
	v_add_f32_e32 v14, 1.0, v14
	v_add_f32_e32 v15, 1.0, v15
	v_rcp_f32_e32 v170, v80
	v_add_f32_e32 v80, 1.0, v171
	v_rcp_f32_e32 v12, v12
	v_rcp_f32_e32 v13, v13
	v_rcp_f32_e32 v14, v14
	v_rcp_f32_e32 v15, v15
	v_rcp_f32_e32 v171, v80
	v_pk_mul_f32 v[8:9], v[82:83], v[8:9]
	v_pk_mul_f32 v[10:11], v[84:85], v[10:11]
	v_mad_u32_u24 v80, v202, s77, v196
	v_ashrrev_i32_e32 v87, 31, v86
	v_readlane_b32 s36, v254, 54
	s_lshl_b32 s0, s16, 8
	v_readlane_b32 s3, v254, 33
	v_pk_mul_f32 v[12:13], v[160:161], v[12:13]
	v_pk_mul_f32 v[14:15], v[162:163], v[14:15]
	v_pk_mul_f32 v[164:165], v[152:153], v[164:165]
	v_pk_mul_f32 v[166:167], v[154:155], v[166:167]
	v_pk_mul_f32 v[168:169], v[156:157], v[168:169]
	v_pk_mul_f32 v[170:171], v[158:159], v[170:171]
	v_cvt_pk_bf16_f32 v8, v8, v9
	v_cvt_pk_bf16_f32 v9, v10, v11
	v_cvt_pk_bf16_f32 v10, v12, v13
	v_cvt_pk_bf16_f32 v11, v14, v15
	v_cvt_pk_bf16_f32 v12, v164, v165
	v_cvt_pk_bf16_f32 v13, v166, v167
	v_cvt_pk_bf16_f32 v14, v168, v169
	v_cvt_pk_bf16_f32 v15, v170, v171
	v_readlane_b32 s100, v254, 33
	s_lshl_b32 s101, s16, 8
	v_readlane_b32 s36, v254, 54
	v_readlane_b32 s37, v254, 55
	s_or_b32 s100, s100, s101
	s_lshl_b32 s100, s100, 1
	s_add_u32 s100, s100, 0x591f200
	s_add_u32 s100, s100, s18
	s_addc_u32 s101, s19, 0
	s_add_u32 s100, s100, s36
	s_addc_u32 s101, s101, s37
	v_and_b32_e32 v164, 15, v194
	v_lshlrev_b32_e32 v164, 11, v164
	v_and_b32_e32 v165, 16, v194
	v_lshl_or_b32 v164, v165, 1, v164
	v_and_b32_e32 v165, 32, v194
	v_lshrrev_b32_e32 v165, 1, v165
	v_or_b32_e32 v164, v164, v165
	v_or_b32_e32 v164, 0x8000, v164
	s_nop 1
	v_permlane16_swap_b32_e32 v8, v10
	v_permlane16_swap_b32_e32 v9, v11
	v_permlane16_swap_b32_e32 v12, v14
	v_permlane16_swap_b32_e32 v13, v15
	global_store_dwordx4 v164, v[8:11], s[100:101] sc1
	global_store_dwordx4 v164, v[12:15], s[100:101] offset:64 sc1
	s_nop 1
	s_mov_b64 s[44:45], 0

.LBB0_990:
	v_mov_b64_e32 v[0:1], v[8:9]
	s_andn2_b64 vcc, exec, s[44:45]
	v_mov_b64_e32 v[2:3], v[10:11]
	v_mov_b64_e32 v[4:5], v[12:13]
	v_mov_b64_e32 v[6:7], v[14:15]
	s_cbranch_vccnz .LBB0_997
	s_cmp_lg_u32 s58, 13
	s_mov_b64 s[44:45], -1
	s_cbranch_scc0 .LBB0_993
	v_mul_f32_e32 v80, 0xbfb8aa3b, v152
	v_exp_f32_e32 v80, v80
	v_mul_f32_e32 v87, 0xbfb8aa3b, v153
	v_exp_f32_e32 v87, v87
	v_mul_f32_e32 v165, 0xbfb8aa3b, v155
	v_add_f32_e32 v80, 1.0, v80
	v_rcp_f32_e32 v164, v80
	v_add_f32_e32 v80, 1.0, v87
	v_mul_f32_e32 v87, 0xbfb8aa3b, v154
	v_exp_f32_e32 v87, v87
	v_exp_f32_e32 v167, v165
	v_rcp_f32_e32 v165, v80
	v_mul_f32_e32 v0, 0xbfb8aa3b, v82
	v_add_f32_e32 v80, 1.0, v87
	v_mul_f32_e32 v87, 0xbfb8aa3b, v156
	v_rcp_f32_e32 v166, v80
	v_add_f32_e32 v80, 1.0, v167
	v_exp_f32_e32 v87, v87
	v_mul_f32_e32 v167, 0xbfb8aa3b, v157
	v_exp_f32_e32 v169, v167
	v_mul_f32_e32 v1, 0xbfb8aa3b, v83
	v_mul_f32_e32 v2, 0xbfb8aa3b, v84
	v_mul_f32_e32 v3, 0xbfb8aa3b, v85
	v_rcp_f32_e32 v167, v80
	v_add_f32_e32 v80, 1.0, v87
	v_mul_f32_e32 v87, 0xbfb8aa3b, v158
	v_exp_f32_e32 v0, v0
	v_exp_f32_e32 v1, v1
	v_exp_f32_e32 v2, v2
	v_exp_f32_e32 v3, v3
	v_mul_f32_e32 v4, 0xbfb8aa3b, v160
	v_mul_f32_e32 v5, 0xbfb8aa3b, v161
	v_mul_f32_e32 v6, 0xbfb8aa3b, v162
	v_mul_f32_e32 v7, 0xbfb8aa3b, v163
	v_rcp_f32_e32 v168, v80
	v_add_f32_e32 v80, 1.0, v169
	v_exp_f32_e32 v87, v87
	v_mul_f32_e32 v169, 0xbfb8aa3b, v159
	v_exp_f32_e32 v4, v4
	v_exp_f32_e32 v5, v5
	v_exp_f32_e32 v6, v6
	v_exp_f32_e32 v7, v7
	v_exp_f32_e32 v171, v169
	v_add_f32_e32 v0, 1.0, v0
	v_add_f32_e32 v1, 1.0, v1
	v_add_f32_e32 v2, 1.0, v2
	v_add_f32_e32 v3, 1.0, v3
	v_rcp_f32_e32 v169, v80
	v_add_f32_e32 v80, 1.0, v87
	v_rcp_f32_e32 v0, v0
	v_rcp_f32_e32 v1, v1
	v_rcp_f32_e32 v2, v2
	v_rcp_f32_e32 v3, v3
	v_add_f32_e32 v4, 1.0, v4
	v_add_f32_e32 v5, 1.0, v5
	v_add_f32_e32 v6, 1.0, v6
	v_add_f32_e32 v7, 1.0, v7
	v_rcp_f32_e32 v170, v80
	v_add_f32_e32 v80, 1.0, v171
	v_rcp_f32_e32 v4, v4
	v_rcp_f32_e32 v5, v5
	v_rcp_f32_e32 v6, v6
	v_rcp_f32_e32 v7, v7
	v_rcp_f32_e32 v171, v80
	v_pk_mul_f32 v[0:1], v[82:83], v[0:1]
	v_pk_mul_f32 v[2:3], v[84:85], v[2:3]
	v_mad_u32_u24 v80, v195, s77, v196
	v_pk_mul_f32 v[4:5], v[160:161], v[4:5]
	v_pk_mul_f32 v[6:7], v[162:163], v[6:7]
	v_pk_mul_f32 v[164:165], v[152:153], v[164:165]
	v_pk_mul_f32 v[166:167], v[154:155], v[166:167]
	v_pk_mul_f32 v[168:169], v[156:157], v[168:169]
	v_pk_mul_f32 v[170:171], v[158:159], v[170:171]
	v_cvt_pk_bf16_f32 v0, v0, v1
	v_cvt_pk_bf16_f32 v1, v2, v3
	v_cvt_pk_bf16_f32 v2, v4, v5
	v_cvt_pk_bf16_f32 v3, v6, v7
	v_cvt_pk_bf16_f32 v4, v164, v165
	v_cvt_pk_bf16_f32 v5, v166, v167
	v_cvt_pk_bf16_f32 v6, v168, v169
	v_cvt_pk_bf16_f32 v7, v170, v171
	v_readlane_b32 s100, v254, 33
	s_lshl_b32 s101, s16, 8
	v_readlane_b32 s44, v254, 54
	v_readlane_b32 s45, v254, 55
	s_or_b32 s100, s100, s101
	s_lshl_b32 s100, s100, 1
	s_add_u32 s100, s100, 0x592f200
	s_add_u32 s100, s100, s18
	s_addc_u32 s101, s19, 0
	s_add_u32 s100, s100, s44
	s_addc_u32 s101, s101, s45
	v_and_b32_e32 v164, 15, v194
	v_lshlrev_b32_e32 v164, 11, v164
	v_and_b32_e32 v165, 16, v194
	v_lshl_or_b32 v164, v165, 1, v164
	v_and_b32_e32 v165, 32, v194
	v_lshrrev_b32_e32 v165, 1, v165
	v_or_b32_e32 v164, v164, v165
	s_nop 1
	v_permlane16_swap_b32_e32 v0, v2
	v_permlane16_swap_b32_e32 v1, v3
	v_permlane16_swap_b32_e32 v4, v6
	v_permlane16_swap_b32_e32 v5, v7
	global_store_dwordx4 v164, v[0:3], s[100:101] sc1
	global_store_dwordx4 v164, v[4:7], s[100:101] offset:64 sc1
	s_nop 1
	s_mov_b64 s[44:45], 0

.LBB0_1049:
	v_mov_b64_e32 v[14:15], v[6:7]
	s_andn2_b64 vcc, exec, s[44:45]
	v_mov_b64_e32 v[12:13], v[4:5]
	v_mov_b64_e32 v[10:11], v[2:3]
	v_mov_b64_e32 v[8:9], v[0:1]
	s_cbranch_vccnz .LBB0_1058
	s_cmp_lg_u32 s58, 13
	s_mov_b64 s[44:45], -1
	s_cbranch_scc0 .LBB0_1054
	v_mul_f32_e32 v80, 0xbfb8aa3b, v152
	v_exp_f32_e32 v80, v80
	v_mul_f32_e32 v87, 0xbfb8aa3b, v153
	v_exp_f32_e32 v87, v87
	v_mul_f32_e32 v165, 0xbfb8aa3b, v155
	v_add_f32_e32 v80, 1.0, v80
	v_rcp_f32_e32 v164, v80
	v_add_f32_e32 v80, 1.0, v87
	v_mul_f32_e32 v87, 0xbfb8aa3b, v154
	v_exp_f32_e32 v87, v87
	v_exp_f32_e32 v167, v165
	v_rcp_f32_e32 v165, v80
	v_mul_f32_e32 v8, 0xbfb8aa3b, v82
	v_add_f32_e32 v80, 1.0, v87
	v_mul_f32_e32 v87, 0xbfb8aa3b, v156
	v_rcp_f32_e32 v166, v80
	v_add_f32_e32 v80, 1.0, v167
	v_exp_f32_e32 v87, v87
	v_mul_f32_e32 v167, 0xbfb8aa3b, v157
	v_exp_f32_e32 v169, v167
	v_mul_f32_e32 v9, 0xbfb8aa3b, v83
	v_mul_f32_e32 v10, 0xbfb8aa3b, v84
	v_mul_f32_e32 v11, 0xbfb8aa3b, v85
	v_rcp_f32_e32 v167, v80
	v_add_f32_e32 v80, 1.0, v87
	v_mul_f32_e32 v87, 0xbfb8aa3b, v158
	v_exp_f32_e32 v8, v8
	v_exp_f32_e32 v9, v9
	v_exp_f32_e32 v10, v10
	v_exp_f32_e32 v11, v11
	v_mul_f32_e32 v12, 0xbfb8aa3b, v160
	v_mul_f32_e32 v13, 0xbfb8aa3b, v161
	v_mul_f32_e32 v14, 0xbfb8aa3b, v162
	v_mul_f32_e32 v15, 0xbfb8aa3b, v163
	v_rcp_f32_e32 v168, v80
	v_add_f32_e32 v80, 1.0, v169
	v_exp_f32_e32 v87, v87
	v_mul_f32_e32 v169, 0xbfb8aa3b, v159
	v_exp_f32_e32 v12, v12
	v_exp_f32_e32 v13, v13
	v_exp_f32_e32 v14, v14
	v_exp_f32_e32 v15, v15
	v_exp_f32_e32 v171, v169
	v_add_f32_e32 v8, 1.0, v8
	v_add_f32_e32 v9, 1.0, v9
	v_add_f32_e32 v10, 1.0, v10
	v_add_f32_e32 v11, 1.0, v11
	v_rcp_f32_e32 v169, v80
	v_add_f32_e32 v80, 1.0, v87
	v_rcp_f32_e32 v8, v8
	v_rcp_f32_e32 v9, v9
	v_rcp_f32_e32 v10, v10
	v_rcp_f32_e32 v11, v11
	v_add_f32_e32 v12, 1.0, v12
	v_add_f32_e32 v13, 1.0, v13
	v_add_f32_e32 v14, 1.0, v14
	v_add_f32_e32 v15, 1.0, v15
	v_rcp_f32_e32 v170, v80
	v_add_f32_e32 v80, 1.0, v171
	v_rcp_f32_e32 v12, v12
	v_rcp_f32_e32 v13, v13
	v_rcp_f32_e32 v14, v14
	v_rcp_f32_e32 v15, v15
	v_rcp_f32_e32 v171, v80
	v_pk_mul_f32 v[8:9], v[82:83], v[8:9]
	v_pk_mul_f32 v[10:11], v[84:85], v[10:11]
	v_mad_u32_u24 v80, v202, s77, v196
	v_ashrrev_i32_e32 v87, 31, v86
	v_readlane_b32 s26, v254, 54
	s_lshl_b32 s0, s16, 8
	v_readlane_b32 s3, v254, 33
	v_pk_mul_f32 v[12:13], v[160:161], v[12:13]
	v_pk_mul_f32 v[14:15], v[162:163], v[14:15]
	v_pk_mul_f32 v[164:165], v[152:153], v[164:165]
	v_pk_mul_f32 v[166:167], v[154:155], v[166:167]
	v_pk_mul_f32 v[168:169], v[156:157], v[168:169]
	v_pk_mul_f32 v[170:171], v[158:159], v[170:171]
	v_cvt_pk_bf16_f32 v8, v8, v9
	v_cvt_pk_bf16_f32 v9, v10, v11
	v_cvt_pk_bf16_f32 v10, v12, v13
	v_cvt_pk_bf16_f32 v11, v14, v15
	v_cvt_pk_bf16_f32 v12, v164, v165
	v_cvt_pk_bf16_f32 v13, v166, v167
	v_cvt_pk_bf16_f32 v14, v168, v169
	v_cvt_pk_bf16_f32 v15, v170, v171
	v_readlane_b32 s100, v254, 33
	s_lshl_b32 s101, s16, 8
	v_readlane_b32 s26, v254, 54
	v_readlane_b32 s27, v254, 55
	s_or_b32 s100, s100, s101
	s_lshl_b32 s100, s100, 1
	s_add_u32 s100, s100, 0x592f200
	s_add_u32 s100, s100, s18
	s_addc_u32 s101, s19, 0
	s_add_u32 s100, s100, s26
	s_addc_u32 s101, s101, s27
	v_and_b32_e32 v164, 15, v194
	v_lshlrev_b32_e32 v164, 11, v164
	v_and_b32_e32 v165, 16, v194
	v_lshl_or_b32 v164, v165, 1, v164
	v_and_b32_e32 v165, 32, v194
	v_lshrrev_b32_e32 v165, 1, v165
	v_or_b32_e32 v164, v164, v165
	v_or_b32_e32 v164, 0x8000, v164
	s_nop 1
	v_permlane16_swap_b32_e32 v8, v10
	v_permlane16_swap_b32_e32 v9, v11
	v_permlane16_swap_b32_e32 v12, v14
	v_permlane16_swap_b32_e32 v13, v15
	global_store_dwordx4 v164, v[8:11], s[100:101] sc1
	global_store_dwordx4 v164, v[12:15], s[100:101] offset:64 sc1
	s_nop 1
	s_mov_b64 s[44:45], 0
